# dead v_readlane pair (fed the hoisted kernarg load) removed from the leading wave group's per-tile path
# speedup vs baseline: 1.0019x; 1.0019x over previous
; #define QSTEP(d, A, B, NA, NB) do { if ((d) + 2 < 12) { NA = KLD((d) + 2, 0); NB = KLD((d) + 2, 1); } SBAR(); \
;     p0 = __builtin_amdgcn_mfma_f32_32x32x16_bf16(A, qr[d], p0, 0, 0, 0); p1 = __builtin_amdgcn_mfma_f32_32x32x16_bf16(B, qr[d], p1, 0, 0, 0); SBAR(); } while (0)
; __device__ __forceinline__ void qkt2(f32x16& p0, f32x16& p1, const char* Ks, const bf16x8* qr, const int* kb4) {
;     ...
;   p0 = f32x16{}; p1 = f32x16{};
;   bf16x8 a0 = KLD(0, 0), b0 = KLD(0, 1), a1 = KLD(1, 0), b1 = KLD(1, 1), a2, b2;
;     ...
;   QSTEP(0, a0, b0, a2, b2); QSTEP(1, a1, b1, a0, b0); QSTEP(2, a2, b2, a1, b1);
;   QSTEP(3, a0, b0, a2, b2); QSTEP(4, a1, b1, a0, b0); QSTEP(5, a2, b2, a1, b1);
;   QSTEP(6, a0, b0, a2, b2); QSTEP(7, a1, b1, a0, b0); QSTEP(8, a2, b2, a1, b1);
;   QSTEP(9, a0, b0, a2, b2); QSTEP(10, a1, b1, a0, b0); QSTEP(11, a2, b2, a1, b1);
;     ...
; }
.LBB0_459:
	ds_read_b128 v[64:67], v210 offset:32768
	ds_read_b128 v[80:83], v210 offset:45056
	ds_read_b128 v[168:171], v209 offset:32768
	ds_read_b128 v[180:183], v209 offset:45056
	ds_read_b128 v[186:189], v208 offset:32768
	ds_read_b128 v[190:193], v208 offset:45056
	s_waitcnt lgkmcnt(4)
	v_mfma_f32_32x32x16_bf16 v[64:79], v[64:67], v[96:99], 0
	v_mfma_f32_32x32x16_bf16 v[80:95], v[80:83], v[96:99], 0
	ds_read_b128 v[194:197], v207 offset:32768
	ds_read_b128 v[214:217], v207 offset:45056
	s_waitcnt lgkmcnt(4)
	v_mfma_f32_32x32x16_bf16 v[64:79], v[168:171], v[100:103], v[64:79]
	v_mfma_f32_32x32x16_bf16 v[80:95], v[180:183], v[100:103], v[80:95]
	ds_read_b128 v[168:171], v210 offset:32896
	ds_read_b128 v[180:183], v210 offset:45184
	s_waitcnt lgkmcnt(4)
	v_mfma_f32_32x32x16_bf16 v[64:79], v[186:189], v[104:107], v[64:79]
	v_mfma_f32_32x32x16_bf16 v[80:95], v[190:193], v[104:107], v[80:95]
	ds_read_b128 v[186:189], v209 offset:32896
	ds_read_b128 v[190:193], v209 offset:45184
	s_waitcnt lgkmcnt(4)
	v_mfma_f32_32x32x16_bf16 v[64:79], v[194:197], v[108:111], v[64:79]
	v_mfma_f32_32x32x16_bf16 v[80:95], v[214:217], v[108:111], v[80:95]
	ds_read_b128 v[194:197], v208 offset:32896
	ds_read_b128 v[214:217], v208 offset:45184
	s_waitcnt lgkmcnt(4)
	v_mfma_f32_32x32x16_bf16 v[64:79], v[168:171], v[112:115], v[64:79]
	v_mfma_f32_32x32x16_bf16 v[80:95], v[180:183], v[112:115], v[80:95]
	ds_read_b128 v[168:171], v207 offset:32896
	ds_read_b128 v[180:183], v207 offset:45184
	s_waitcnt lgkmcnt(4)
	v_mfma_f32_32x32x16_bf16 v[64:79], v[186:189], v[116:119], v[64:79]
	v_mfma_f32_32x32x16_bf16 v[80:95], v[190:193], v[116:119], v[80:95]
	ds_read_b128 v[186:189], v210 offset:33024
	ds_read_b128 v[190:193], v210 offset:45312
	s_waitcnt lgkmcnt(4)
	v_mfma_f32_32x32x16_bf16 v[64:79], v[194:197], v[120:123], v[64:79]
	v_mfma_f32_32x32x16_bf16 v[80:95], v[214:217], v[120:123], v[80:95]
	ds_read_b128 v[194:197], v209 offset:33024
	ds_read_b128 v[214:217], v209 offset:45312
	s_waitcnt lgkmcnt(4)
	v_mfma_f32_32x32x16_bf16 v[64:79], v[168:171], v[124:127], v[64:79]
	v_mfma_f32_32x32x16_bf16 v[80:95], v[180:183], v[124:127], v[80:95]
	ds_read_b128 v[168:171], v208 offset:33024
	ds_read_b128 v[180:183], v208 offset:45312
	s_waitcnt lgkmcnt(4)
	v_mfma_f32_32x32x16_bf16 v[64:79], v[186:189], v[132:135], v[64:79]
	v_mfma_f32_32x32x16_bf16 v[80:95], v[190:193], v[132:135], v[80:95]
	ds_read_b128 v[186:189], v207 offset:33024
	ds_read_b128 v[190:193], v207 offset:45312
	s_waitcnt lgkmcnt(4)
	v_mfma_f32_32x32x16_bf16 v[64:79], v[194:197], v[140:143], v[64:79]
	v_mfma_f32_32x32x16_bf16 v[80:95], v[214:217], v[140:143], v[80:95]
	s_waitcnt lgkmcnt(2)
	v_mfma_f32_32x32x16_bf16 v[64:79], v[168:171], v[128:131], v[64:79]
	v_mfma_f32_32x32x16_bf16 v[80:95], v[180:183], v[128:131], v[80:95]
	s_waitcnt lgkmcnt(0)
	v_mfma_f32_32x32x16_bf16 v[64:79], v[186:189], v[136:139], v[64:79]
	v_mfma_f32_32x32x16_bf16 v[80:95], v[190:193], v[136:139], v[80:95]
	s_cmp_eq_u32 s42, 0
	s_cbranch_scc1 .Lmask0_a
	s_nop 9
